# v21 + FFN-up K-loop: LDS-DMA addresses scalarized (SGPR base + 32-bit lane offset, saddr form), 16 64-bit VALU adds per iteration removed from the load segments
# speedup vs baseline: 1.0062x; 1.0028x over previous
.LBB0_1158:
	s_add_u32 s34, s62, 0x100
	s_addc_u32 s35, s63, 0
	s_add_i32 s67, 0, 0x10000
	s_cmp_eq_u32 s6, 28
	s_cselect_b32 s89, s23, s35
	s_cselect_b32 s88, s61, s34
	s_cselect_b32 vcc_hi, s91, s3
	s_cselect_b32 vcc_lo, s93, s2
	s_add_i32 s76, 0, 0x14000
	v_add_u32_e32 v142, s67, v191
	v_add_u32_e32 v158, s76, v191
	ds_read_b128 v[130:133], v142
	ds_read_b128 v[134:137], v142 offset:1024
	ds_read_b128 v[138:141], v142 offset:2048
	ds_read_b128 v[142:145], v142 offset:3072
	ds_read_b128 v[146:149], v158
	ds_read_b128 v[150:153], v158 offset:1024
	ds_read_b128 v[154:157], v158 offset:2048
	ds_read_b128 v[158:161], v158 offset:3072
	s_add_i32 m0, s17, 0xc000
	ds_read_b128 v[162:165], v224
	ds_read_b128 v[166:169], v224 offset:1024
	ds_read_b128 v[170:173], v224 offset:2048
	ds_read_b128 v[178:181], v224 offset:3072
	ds_read_b128 v[202:205], v224 offset:4096
	ds_read_b128 v[206:209], v224 offset:5120
	ds_read_b128 v[226:229], v224 offset:6144
	ds_read_b128 v[230:233], v224 offset:7168
	global_load_lds_dwordx4 v184, s[62:63]
	s_add_i32 m0, s17, 0xe000
	s_nop 0
	global_load_lds_dwordx4 v186, s[62:63]
	s_waitcnt vmcnt(8)
	s_waitcnt lgkmcnt(0)
	s_barrier
	s_setprio 1
	s_waitcnt lgkmcnt(0)
	v_mfma_f32_16x16x32_bf16 v[126:129], v[130:133], v[162:165], v[126:129]
	v_mfma_f32_16x16x32_bf16 v[56:59], v[138:141], v[162:165], v[56:59]
	v_mfma_f32_16x16x32_bf16 v[122:125], v[130:133], v[170:173], v[122:125]
	v_mfma_f32_16x16x32_bf16 v[52:55], v[138:141], v[170:173], v[52:55]
	v_mfma_f32_16x16x32_bf16 v[118:121], v[130:133], v[202:205], v[118:121]
	v_mfma_f32_16x16x32_bf16 v[60:63], v[138:141], v[202:205], v[60:63]
	v_mfma_f32_16x16x32_bf16 v[114:117], v[130:133], v[226:229], v[114:117]
	v_mfma_f32_16x16x32_bf16 v[44:47], v[138:141], v[226:229], v[44:47]
	v_mfma_f32_16x16x32_bf16 v[126:129], v[134:137], v[166:169], v[126:129]
	v_mfma_f32_16x16x32_bf16 v[56:59], v[142:145], v[166:169], v[56:59]
	v_mfma_f32_16x16x32_bf16 v[122:125], v[134:137], v[178:181], v[122:125]
	v_mfma_f32_16x16x32_bf16 v[52:55], v[142:145], v[178:181], v[52:55]
	v_mfma_f32_16x16x32_bf16 v[118:121], v[134:137], v[206:209], v[118:121]
	v_mfma_f32_16x16x32_bf16 v[60:63], v[142:145], v[206:209], v[60:63]
	v_mfma_f32_16x16x32_bf16 v[114:117], v[134:137], v[230:233], v[114:117]
	v_mfma_f32_16x16x32_bf16 v[44:47], v[142:145], v[230:233], v[44:47]
	s_setprio 0
	s_setprio 1
	v_mfma_f32_16x16x32_bf16 v[110:113], v[146:149], v[162:165], v[110:113]
	v_mfma_f32_16x16x32_bf16 v[40:43], v[154:157], v[162:165], v[40:43]
	v_mfma_f32_16x16x32_bf16 v[106:109], v[146:149], v[170:173], v[106:109]
	v_mfma_f32_16x16x32_bf16 v[36:39], v[154:157], v[170:173], v[36:39]
	v_mfma_f32_16x16x32_bf16 v[102:105], v[146:149], v[202:205], v[102:105]
	v_mfma_f32_16x16x32_bf16 v[48:51], v[154:157], v[202:205], v[48:51]
	v_mfma_f32_16x16x32_bf16 v[98:101], v[146:149], v[226:229], v[98:101]
	v_mfma_f32_16x16x32_bf16 v[32:35], v[154:157], v[226:229], v[32:35]
	v_mfma_f32_16x16x32_bf16 v[110:113], v[150:153], v[166:169], v[110:113]
	v_mfma_f32_16x16x32_bf16 v[40:43], v[158:161], v[166:169], v[40:43]
	v_mfma_f32_16x16x32_bf16 v[106:109], v[150:153], v[178:181], v[106:109]
	v_mfma_f32_16x16x32_bf16 v[36:39], v[158:161], v[178:181], v[36:39]
	v_mfma_f32_16x16x32_bf16 v[102:105], v[150:153], v[206:209], v[102:105]
	v_mfma_f32_16x16x32_bf16 v[48:51], v[158:161], v[206:209], v[48:51]
	v_mfma_f32_16x16x32_bf16 v[98:101], v[150:153], v[230:233], v[98:101]
	v_mfma_f32_16x16x32_bf16 v[32:35], v[158:161], v[230:233], v[32:35]
	s_setprio 0
	s_barrier
	s_add_i32 s62, s67, s5
	s_mov_b32 m0, s62
	ds_read_b128 v[162:165], v224 offset:16384
	ds_read_b128 v[166:169], v224 offset:17408
	ds_read_b128 v[170:173], v224 offset:18432
	ds_read_b128 v[178:181], v224 offset:19456
	ds_read_b128 v[202:205], v224 offset:20480
	ds_read_b128 v[206:209], v224 offset:21504
	ds_read_b128 v[226:229], v224 offset:22528
	ds_read_b128 v[230:233], v224 offset:23552
	global_load_lds_dwordx4 v96, vcc
	s_add_i32 m0, s62, 0x2000
	s_add_u32 s62, vcc_lo, 0x80000
	s_addc_u32 s63, vcc_hi, 0
	s_add_i32 s67, s76, s5
	global_load_lds_dwordx4 v182, vcc
	s_mov_b32 m0, s67
	s_nop 0
	global_load_lds_dwordx4 v96, s[62:63]
	s_add_i32 m0, s67, 0x2000
	s_nop 0
	global_load_lds_dwordx4 v182, s[62:63]
	s_mov_b32 m0, s17
	s_nop 0
	global_load_lds_dwordx4 v174, s[88:89]
	s_mov_b32 m0, s18
	s_nop 0
	global_load_lds_dwordx4 v176, s[88:89]
	s_waitcnt vmcnt(8)
	s_waitcnt lgkmcnt(0)
	s_barrier
	s_setprio 1
	s_waitcnt lgkmcnt(0)
	v_mfma_f32_16x16x32_bf16 v[92:95], v[130:133], v[162:165], v[92:95]
	v_mfma_f32_16x16x32_bf16 v[24:27], v[138:141], v[162:165], v[24:27]
	v_mfma_f32_16x16x32_bf16 v[88:91], v[130:133], v[170:173], v[88:91]
	v_mfma_f32_16x16x32_bf16 v[28:31], v[138:141], v[170:173], v[28:31]
	v_mfma_f32_16x16x32_bf16 v[84:87], v[130:133], v[202:205], v[84:87]
	v_mfma_f32_16x16x32_bf16 v[16:19], v[138:141], v[202:205], v[16:19]
	v_mfma_f32_16x16x32_bf16 v[80:83], v[130:133], v[226:229], v[80:83]
	v_mfma_f32_16x16x32_bf16 v[20:23], v[138:141], v[226:229], v[20:23]
	v_mfma_f32_16x16x32_bf16 v[92:95], v[134:137], v[166:169], v[92:95]
	v_mfma_f32_16x16x32_bf16 v[24:27], v[142:145], v[166:169], v[24:27]
	v_mfma_f32_16x16x32_bf16 v[88:91], v[134:137], v[178:181], v[88:91]
	v_mfma_f32_16x16x32_bf16 v[28:31], v[142:145], v[178:181], v[28:31]
	v_mfma_f32_16x16x32_bf16 v[84:87], v[134:137], v[206:209], v[84:87]
	v_mfma_f32_16x16x32_bf16 v[16:19], v[142:145], v[206:209], v[16:19]
	v_mfma_f32_16x16x32_bf16 v[80:83], v[134:137], v[230:233], v[80:83]
	v_mfma_f32_16x16x32_bf16 v[20:23], v[142:145], v[230:233], v[20:23]
	s_setprio 0
	s_setprio 1
	v_mfma_f32_16x16x32_bf16 v[76:79], v[146:149], v[162:165], v[76:79]
	v_mfma_f32_16x16x32_bf16 v[12:15], v[154:157], v[162:165], v[12:15]
	v_mfma_f32_16x16x32_bf16 v[72:75], v[146:149], v[170:173], v[72:75]
	v_mfma_f32_16x16x32_bf16 v[8:11], v[154:157], v[170:173], v[8:11]
	v_mfma_f32_16x16x32_bf16 v[68:71], v[146:149], v[202:205], v[68:71]
	v_mfma_f32_16x16x32_bf16 v[0:3], v[154:157], v[202:205], v[0:3]
	v_mfma_f32_16x16x32_bf16 v[64:67], v[146:149], v[226:229], v[64:67]
	v_mfma_f32_16x16x32_bf16 v[4:7], v[154:157], v[226:229], v[4:7]
	v_mfma_f32_16x16x32_bf16 v[76:79], v[150:153], v[166:169], v[76:79]
	v_mfma_f32_16x16x32_bf16 v[12:15], v[158:161], v[166:169], v[12:15]
	v_mfma_f32_16x16x32_bf16 v[72:75], v[150:153], v[178:181], v[72:75]
	v_mfma_f32_16x16x32_bf16 v[8:11], v[158:161], v[178:181], v[8:11]
	v_mfma_f32_16x16x32_bf16 v[68:71], v[150:153], v[206:209], v[68:71]
	v_mfma_f32_16x16x32_bf16 v[0:3], v[158:161], v[206:209], v[0:3]
	v_mfma_f32_16x16x32_bf16 v[64:67], v[150:153], v[230:233], v[64:67]
	v_mfma_f32_16x16x32_bf16 v[4:7], v[158:161], v[230:233], v[4:7]
	s_setprio 0
	s_barrier
	s_add_i32 s67, 0, 0x18000
	s_add_i32 s76, 0, 0x1c000
	v_add_u32_e32 v142, s67, v191
	v_add_u32_e32 v158, s76, v191
	ds_read_b128 v[130:133], v142
	ds_read_b128 v[134:137], v142 offset:1024
	ds_read_b128 v[138:141], v142 offset:2048
	ds_read_b128 v[142:145], v142 offset:3072
	ds_read_b128 v[146:149], v158
	ds_read_b128 v[150:153], v158 offset:1024
	ds_read_b128 v[154:157], v158 offset:2048
	ds_read_b128 v[158:161], v158 offset:3072
	s_add_u32 s62, s88, 0x80000
	s_addc_u32 s63, s89, 0
	s_mov_b32 m0, s19
	ds_read_b128 v[162:165], v224 offset:32768
	ds_read_b128 v[166:169], v224 offset:33792
	ds_read_b128 v[170:173], v224 offset:34816
	ds_read_b128 v[178:181], v224 offset:35840
	ds_read_b128 v[202:205], v224 offset:36864
	ds_read_b128 v[206:209], v224 offset:37888
	ds_read_b128 v[226:229], v224 offset:38912
	ds_read_b128 v[230:233], v224 offset:39936
	global_load_lds_dwordx4 v174, s[62:63]
	s_mov_b32 m0, s20
	s_nop 0
	global_load_lds_dwordx4 v176, s[62:63]
	s_waitcnt vmcnt(8)
	s_waitcnt lgkmcnt(0)
	s_barrier
	s_setprio 1
	s_waitcnt lgkmcnt(0)
	v_mfma_f32_16x16x32_bf16 v[126:129], v[130:133], v[162:165], v[126:129]
	v_mfma_f32_16x16x32_bf16 v[56:59], v[138:141], v[162:165], v[56:59]
	v_mfma_f32_16x16x32_bf16 v[122:125], v[130:133], v[170:173], v[122:125]
	v_mfma_f32_16x16x32_bf16 v[52:55], v[138:141], v[170:173], v[52:55]
	v_mfma_f32_16x16x32_bf16 v[118:121], v[130:133], v[202:205], v[118:121]
	v_mfma_f32_16x16x32_bf16 v[60:63], v[138:141], v[202:205], v[60:63]
	v_mfma_f32_16x16x32_bf16 v[114:117], v[130:133], v[226:229], v[114:117]
	v_mfma_f32_16x16x32_bf16 v[44:47], v[138:141], v[226:229], v[44:47]
	v_mfma_f32_16x16x32_bf16 v[126:129], v[134:137], v[166:169], v[126:129]
	v_mfma_f32_16x16x32_bf16 v[56:59], v[142:145], v[166:169], v[56:59]
	v_mfma_f32_16x16x32_bf16 v[122:125], v[134:137], v[178:181], v[122:125]
	v_mfma_f32_16x16x32_bf16 v[52:55], v[142:145], v[178:181], v[52:55]
	v_mfma_f32_16x16x32_bf16 v[118:121], v[134:137], v[206:209], v[118:121]
	v_mfma_f32_16x16x32_bf16 v[60:63], v[142:145], v[206:209], v[60:63]
	v_mfma_f32_16x16x32_bf16 v[114:117], v[134:137], v[230:233], v[114:117]
	v_mfma_f32_16x16x32_bf16 v[44:47], v[142:145], v[230:233], v[44:47]
	s_setprio 0
	s_setprio 1
	v_mfma_f32_16x16x32_bf16 v[110:113], v[146:149], v[162:165], v[110:113]
	v_mfma_f32_16x16x32_bf16 v[40:43], v[154:157], v[162:165], v[40:43]
	v_mfma_f32_16x16x32_bf16 v[106:109], v[146:149], v[170:173], v[106:109]
	v_mfma_f32_16x16x32_bf16 v[36:39], v[154:157], v[170:173], v[36:39]
	v_mfma_f32_16x16x32_bf16 v[102:105], v[146:149], v[202:205], v[102:105]
	v_mfma_f32_16x16x32_bf16 v[48:51], v[154:157], v[202:205], v[48:51]
	v_mfma_f32_16x16x32_bf16 v[98:101], v[146:149], v[226:229], v[98:101]
	v_mfma_f32_16x16x32_bf16 v[32:35], v[154:157], v[226:229], v[32:35]
	v_mfma_f32_16x16x32_bf16 v[110:113], v[150:153], v[166:169], v[110:113]
	v_mfma_f32_16x16x32_bf16 v[40:43], v[158:161], v[166:169], v[40:43]
	v_mfma_f32_16x16x32_bf16 v[106:109], v[150:153], v[178:181], v[106:109]
	v_mfma_f32_16x16x32_bf16 v[36:39], v[158:161], v[178:181], v[36:39]
	v_mfma_f32_16x16x32_bf16 v[102:105], v[150:153], v[206:209], v[102:105]
	v_mfma_f32_16x16x32_bf16 v[48:51], v[158:161], v[206:209], v[48:51]
	v_mfma_f32_16x16x32_bf16 v[98:101], v[150:153], v[230:233], v[98:101]
	v_mfma_f32_16x16x32_bf16 v[32:35], v[158:161], v[230:233], v[32:35]
	s_setprio 0
	s_barrier
	s_add_u32 s62, vcc_lo, s30
	s_addc_u32 s63, vcc_hi, s31
	s_add_i32 m0, s67, s5
	ds_read_b128 v[162:165], v224 offset:49152
	ds_read_b128 v[166:169], v224 offset:50176
	ds_read_b128 v[170:173], v224 offset:51200
	ds_read_b128 v[178:181], v224 offset:52224
	ds_read_b128 v[202:205], v224 offset:53248
	ds_read_b128 v[206:209], v224 offset:54272
	ds_read_b128 v[226:229], v224 offset:55296
	ds_read_b128 v[230:233], v224 offset:56320
	global_load_lds_dwordx4 v96, s[62:63]
	s_add_i32 m0, m0, 0x2000
	s_add_i32 s67, s76, s5
	global_load_lds_dwordx4 v182, s[62:63]
	s_add_u32 s62, vcc_lo, 0x80080
	s_addc_u32 s63, vcc_hi, 0
	s_mov_b32 m0, s67
	s_nop 0
	global_load_lds_dwordx4 v96, s[62:63]
	s_add_i32 m0, s67, 0x2000
	s_nop 0
	global_load_lds_dwordx4 v182, s[62:63]
	s_add_u32 s62, s88, s30
	s_addc_u32 s63, s89, s31
	s_mov_b32 m0, s36
	s_nop 0
	global_load_lds_dwordx4 v174, s[62:63]
	s_mov_b32 m0, s37
	s_nop 0
	global_load_lds_dwordx4 v176, s[62:63]
	s_waitcnt vmcnt(8)
	s_waitcnt lgkmcnt(0)
	s_barrier
	s_setprio 1
	s_waitcnt lgkmcnt(0)
	v_mfma_f32_16x16x32_bf16 v[92:95], v[130:133], v[162:165], v[92:95]
	v_mfma_f32_16x16x32_bf16 v[24:27], v[138:141], v[162:165], v[24:27]
	v_mfma_f32_16x16x32_bf16 v[88:91], v[130:133], v[170:173], v[88:91]
	v_mfma_f32_16x16x32_bf16 v[28:31], v[138:141], v[170:173], v[28:31]
	v_mfma_f32_16x16x32_bf16 v[84:87], v[130:133], v[202:205], v[84:87]
	v_mfma_f32_16x16x32_bf16 v[16:19], v[138:141], v[202:205], v[16:19]
	v_mfma_f32_16x16x32_bf16 v[80:83], v[130:133], v[226:229], v[80:83]
	v_mfma_f32_16x16x32_bf16 v[20:23], v[138:141], v[226:229], v[20:23]
	v_mfma_f32_16x16x32_bf16 v[92:95], v[134:137], v[166:169], v[92:95]
	v_mfma_f32_16x16x32_bf16 v[24:27], v[142:145], v[166:169], v[24:27]
	v_mfma_f32_16x16x32_bf16 v[88:91], v[134:137], v[178:181], v[88:91]
	v_mfma_f32_16x16x32_bf16 v[28:31], v[142:145], v[178:181], v[28:31]
	v_mfma_f32_16x16x32_bf16 v[84:87], v[134:137], v[206:209], v[84:87]
	v_mfma_f32_16x16x32_bf16 v[16:19], v[142:145], v[206:209], v[16:19]
	v_mfma_f32_16x16x32_bf16 v[80:83], v[134:137], v[230:233], v[80:83]
	v_mfma_f32_16x16x32_bf16 v[20:23], v[142:145], v[230:233], v[20:23]
	s_setprio 0
	s_setprio 1
	v_mfma_f32_16x16x32_bf16 v[76:79], v[146:149], v[162:165], v[76:79]
	v_mfma_f32_16x16x32_bf16 v[12:15], v[154:157], v[162:165], v[12:15]
	v_mfma_f32_16x16x32_bf16 v[72:75], v[146:149], v[170:173], v[72:75]
	v_mfma_f32_16x16x32_bf16 v[8:11], v[154:157], v[170:173], v[8:11]
	v_mfma_f32_16x16x32_bf16 v[68:71], v[146:149], v[202:205], v[68:71]
	v_mfma_f32_16x16x32_bf16 v[0:3], v[154:157], v[202:205], v[0:3]
	v_mfma_f32_16x16x32_bf16 v[64:67], v[146:149], v[226:229], v[64:67]
	v_mfma_f32_16x16x32_bf16 v[4:7], v[154:157], v[226:229], v[4:7]
	v_mfma_f32_16x16x32_bf16 v[76:79], v[150:153], v[166:169], v[76:79]
	v_mfma_f32_16x16x32_bf16 v[12:15], v[158:161], v[166:169], v[12:15]
	v_mfma_f32_16x16x32_bf16 v[72:75], v[150:153], v[178:181], v[72:75]
	v_mfma_f32_16x16x32_bf16 v[8:11], v[158:161], v[178:181], v[8:11]
	v_mfma_f32_16x16x32_bf16 v[68:71], v[150:153], v[206:209], v[68:71]
	v_mfma_f32_16x16x32_bf16 v[0:3], v[158:161], v[206:209], v[0:3]
	v_mfma_f32_16x16x32_bf16 v[64:67], v[150:153], v[230:233], v[64:67]
	v_mfma_f32_16x16x32_bf16 v[4:7], v[158:161], v[230:233], v[4:7]
	s_setprio 0
	s_barrier
	s_add_i32 s6, s6, 2
	s_add_u32 s2, s2, 0x100
	s_addc_u32 s3, s3, 0
	s_cmp_gt_u32 s6, 29
	s_mov_b64 s[62:63], s[34:35]
	s_cbranch_scc0 .LBB0_1158
	s_and_b64 vcc, exec, s[24:25]
	s_cbranch_vccz .LBB0_1161
	s_barrier
.LBB0_1161:
	s_branch .Lmy_pad3
	s_nop 0
	s_nop 0
	s_nop 0
	s_nop 0
	s_nop 0
	s_nop 0
	s_nop 0
	s_nop 0
	s_nop 0
	s_nop 0
	s_nop 0
	s_nop 0
	s_nop 0
	s_nop 0
	s_nop 0
	s_nop 0
	s_nop 0
	s_nop 0
	s_nop 0
	s_nop 0
	s_nop 0
	s_nop 0
	s_nop 0
	s_nop 0
	s_nop 0
	s_nop 0
	s_nop 0
	s_nop 0
	s_nop 0
	s_nop 0
	s_nop 0
	s_nop 0
	s_nop 0
	s_nop 0
	s_nop 0
	s_nop 0
	s_nop 0
	s_nop 0
	s_nop 0
	s_nop 0
	s_nop 0
	s_nop 0
	s_nop 0
	s_nop 0
	s_nop 0
	s_nop 0
	s_nop 0
	s_nop 0
	s_nop 0
	s_nop 0
	s_nop 0
	s_nop 0
